# prologue phase: rope-table job also moved off the weight-conversion-heavy workgroups 0..127 onto 128..255
# speedup vs baseline: 1.0047x; 1.0017x over previous
;     DI float* rope() const { return (float*)(ws + WS_ROPE); }
; DI void phase_prep(Frame& F) {
;     ...
;     for (int i = blockIdx.x * NT + F.tid; i < S * 16; i += gridDim.x * NT) {
;         const int t = i >> 4, j = i & 15; const float inv = 1.0f / powf(10000.0f, (float)(2 * j) / 32.0f); const float ang = (float)t * inv;
;         F.rope()[i] = cosf(ang); F.rope()[S * 16 + i] = sinf(ang);
;     }
.LBB0_2066:
	s_sub_i32 s8, s2, 128
	s_lshl_b32 s8, s8, 9
	s_cmp_lt_u32 s2, 128
	s_cselect_b32 s8, 0x10000, s8
	v_add_u32_e32 v2, s8, v232
	s_mov_b32 s8, 0x10000
	v_cmp_gt_i32_e32 vcc, s8, v2
	s_and_saveexec_b64 s[8:9], vcc
	s_cbranch_execz .LBB0_2077
	s_add_u32 s10, s76, 0xf600000
	v_readlane_b32 s17, v254, 12
	s_addc_u32 s11, s77, 0
	s_sub_i32 s17, s17, 0x20000
	s_lshl_b32 s22, s16, 9
	v_lshl_add_u32 v6, v232, 1, s17
	s_lshl_b32 s23, s16, 10
	s_mov_b64 s[50:51], 0
	s_branch .LBB0_2069
